# stack: counted lgkm waits extended through the LDS staging writes (last PV MFMA before the drain)
# baseline (speedup 1.0000x reference)
.LBB0_348:
	s_or_b64 exec, exec, s[2:3]
	v_add_u32_e32 v180, s54, v181
	ds_read_b64_tr_b16 v[196:197], v180 offset:0
	ds_read_b64_tr_b16 v[198:199], v180 offset:0x800
	ds_read_b64_tr_b16 v[200:201], v180 offset:0x1000
	ds_read_b64_tr_b16 v[202:203], v180 offset:0x1800
	ds_read_b64_tr_b16 v[204:205], v180 offset:0x2000
	ds_read_b64_tr_b16 v[206:207], v180 offset:0x2800
	ds_read_b64_tr_b16 v[208:209], v180 offset:0x3000
	ds_read_b64_tr_b16 v[210:211], v180 offset:0x3800
	s_addk_i32 s82, 0x80
	s_waitcnt lgkmcnt(6)
	v_mfma_f32_32x32x16_bf16 v[50:65], v[134:137], v[196:199], v[50:65]
	v_exp_f32_e32 v213, v66
	v_exp_f32_e32 v215, v67
	ds_read_b64_tr_b16 v[66:67], v180 offset:0x200
	v_exp_f32_e32 v217, v68
	v_exp_f32_e32 v221, v69
	ds_read_b64_tr_b16 v[68:69], v180 offset:0xa00
	v_exp_f32_e32 v212, v82
	s_waitcnt lgkmcnt(6)
	v_mfma_f32_32x32x16_bf16 v[50:65], v[138:141], v[200:203], v[50:65]
	v_exp_f32_e32 v214, v83
	ds_read_b64_tr_b16 v[82:83], v180 offset:0x1200
	v_exp_f32_e32 v216, v84
	v_exp_f32_e32 v218, v85
	ds_read_b64_tr_b16 v[84:85], v180 offset:0x1a00
	ds_read_b64_tr_b16 v[196:197], v180 offset:0x2200
	ds_read_b64_tr_b16 v[198:199], v180 offset:0x2a00
	s_waitcnt lgkmcnt(8)
	v_mfma_f32_32x32x16_bf16 v[50:65], v[126:129], v[204:207], v[50:65]
	ds_read_b64_tr_b16 v[200:201], v180 offset:0x3200
	ds_read_b64_tr_b16 v[202:203], v180 offset:0x3a00
	s_waitcnt lgkmcnt(8)
	v_mfma_f32_32x32x16_bf16 v[50:65], v[130:133], v[208:211], v[50:65]
	s_waitcnt lgkmcnt(6)
	v_mfma_f32_32x32x16_bf16 v[34:49], v[134:137], v[66:69], v[34:49]
	ds_read_b64_tr_b16 v[66:67], v180 offset:0x400
	ds_read_b64_tr_b16 v[68:69], v180 offset:0xc00
	v_exp_f32_e32 v205, v70
	v_exp_f32_e32 v207, v71
	ds_read_b64_tr_b16 v[70:71], v180 offset:0x1400
	v_exp_f32_e32 v209, v72
	v_exp_f32_e32 v211, v73
	s_waitcnt lgkmcnt(7)
	v_mfma_f32_32x32x16_bf16 v[34:49], v[138:141], v[82:85], v[34:49]
	ds_read_b64_tr_b16 v[72:73], v180 offset:0x1c00
	ds_read_b64_tr_b16 v[82:83], v180 offset:0x2400
	ds_read_b64_tr_b16 v[84:85], v180 offset:0x2c00
	v_exp_f32_e32 v204, v86
	v_exp_f32_e32 v206, v87
	ds_read_b64_tr_b16 v[86:87], v180 offset:0x3400
	v_exp_f32_e32 v208, v88
	s_waitcnt lgkmcnt(9)
	v_mfma_f32_32x32x16_bf16 v[34:49], v[126:129], v[196:199], v[34:49]
	v_exp_f32_e32 v210, v89
	ds_read_b64_tr_b16 v[88:89], v180 offset:0x3c00
	s_waitcnt lgkmcnt(8)
	v_mfma_f32_32x32x16_bf16 v[34:49], v[130:133], v[200:203], v[34:49]
	s_waitcnt lgkmcnt(6)
	v_mfma_f32_32x32x16_bf16 v[18:33], v[134:137], v[66:69], v[18:33]
	ds_read_b64_tr_b16 v[66:67], v180 offset:0x600
	ds_read_b64_tr_b16 v[68:69], v180 offset:0xe00
	v_exp_f32_e32 v197, v74
	v_exp_f32_e32 v199, v75
	v_exp_f32_e32 v201, v76
	v_exp_f32_e32 v203, v77
	v_exp_f32_e32 v196, v90
	s_waitcnt lgkmcnt(6)
	v_mfma_f32_32x32x16_bf16 v[18:33], v[138:141], v[70:73], v[18:33]
	ds_read_b64_tr_b16 v[70:71], v180 offset:0x1600
	ds_read_b64_tr_b16 v[72:73], v180 offset:0x1e00
	ds_read_b64_tr_b16 v[74:75], v180 offset:0x2600
	ds_read_b64_tr_b16 v[76:77], v180 offset:0x2e00
	v_exp_f32_e32 v198, v91
	v_exp_f32_e32 v200, v92
	v_exp_f32_e32 v202, v93
	s_waitcnt lgkmcnt(8)
	v_mfma_f32_32x32x16_bf16 v[18:33], v[126:129], v[82:85], v[18:33]
	ds_read_b64_tr_b16 v[82:83], v180 offset:0x3600
	ds_read_b64_tr_b16 v[84:85], v180 offset:0x3e00
	s_waitcnt lgkmcnt(8)
	v_mfma_f32_32x32x16_bf16 v[18:33], v[130:133], v[86:89], v[18:33]
	s_waitcnt lgkmcnt(6)
	v_mfma_f32_32x32x16_bf16 v[2:17], v[134:137], v[66:69], v[2:17]
	v_add_u32_e32 v182, s56, v183
	v_exp_f32_e32 v222, v94
	v_exp_f32_e32 v223, v78
	v_exp_f32_e32 v224, v95
	s_waitcnt lgkmcnt(4)
	v_mfma_f32_32x32x16_bf16 v[2:17], v[138:141], v[70:73], v[2:17]
	v_exp_f32_e32 v226, v79
	v_exp_f32_e32 v227, v96
	v_exp_f32_e32 v228, v80
	v_exp_f32_e32 v229, v97
	v_exp_f32_e32 v230, v81
	s_waitcnt vmcnt(0)
	ds_write_b128 v235, v[146:149] offset:32768
	ds_write_b128 v182, v[142:145]
	ds_write_b128 v182, v[154:157] offset:8192
	s_waitcnt lgkmcnt(5)
	v_mfma_f32_32x32x16_bf16 v[2:17], v[126:129], v[74:77], v[2:17]
	s_waitcnt lgkmcnt(0)
	s_barrier
	v_mfma_f32_32x32x16_bf16 v[2:17], v[130:133], v[82:85], v[2:17]
	s_mov_b32 s80, s54
	s_mov_b32 s54, s55
	s_mov_b32 s55, s56
	s_mov_b32 s56, s80
	s_cmp_eq_u32 s82, s99
	s_cbranch_scc1 .Lattn_refill_b
